# overlap across the chunk barrier: scan waves 0-3 arrive at the end-of-chunk barrier right after their MFMAs; the y epilogue runs after it, in their S1 slack
# speedup vs baseline: 1.0136x; 1.0136x over previous
; #define LDS_BARRIER() do { asm volatile("s_waitcnt lgkmcnt(0)" ::: "memory"); __builtin_amdgcn_s_barrier(); asm volatile("" ::: "memory"); } while (0)
; DI void ssd_scan_phase(bf16_t* P, const bf16_t* BT, const bf16_t* Cc, const bf16_t* CB, const float* dt, const float* acs,
;                        const float* cw, const float* cb, const float* Dp, char* lds, bool dry, int mode, float* Sbuf) {
;     ...
;       __builtin_amdgcn_sched_barrier(0);
;       LDS_BARRIER();
;       int lq = l31, hq = h;
;       asm volatile("" : "+v"(lq), "+v"(hq));
;       if (wave < 4) {
;        if (mode == 0) {
;         const int lt = wave;
.LBB0_1101:
	s_waitcnt lgkmcnt(0)
	s_barrier
	v_mov_b32_e32 v197, v133
	v_mov_b32_e32 v174, v175
	s_and_saveexec_b64 s[80:81], s[40:41]
	s_xor_b64 s[80:81], exec, s[80:81]
	s_cbranch_execz .LBB0_1107
	s_and_b64 vcc, exec, s[56:57]
	s_cbranch_vccnz .LBB0_1106
; #define MFMA(a, b, c) __builtin_amdgcn_mfma_f32_32x32x16_bf16((a), (b), (c), 0, 0, 0)
; DI void ssd_scan_phase(bf16_t* P, const bf16_t* BT, const bf16_t* Cc, const bf16_t* CB, const float* dt, const float* acs,
;                        const float* cw, const float* cb, const float* Dp, char* lds, bool dry, int mode, float* Sbuf) {
;     ...
;         const int lt = wave;
;         f32x16 ad, ao;
; #pragma unroll
;         for (int i = 0; i < 16; ++i) { ad[i] = 0.f; ao[i] = 0.f; }
;         const char* stb = sSt + (c & 1) * 8192;
; #pragma unroll
;         for (int kk = 0; kk < 8; ++kk) {
;           const bf16x8 yf = *(const bf16x8*)(sCBL + swz128(32 * lt + lq, 2 * kk + hq));
;           const bf16x8 xf = *(const bf16x8*)(sXdt + swz128(lq, 2 * kk + hq));
;           ad = MFMA(xf, yf, ad);
;           const bf16x8 yf2 = *(const bf16x8*)(sC + swz128(32 * lt + lq, 2 * kk + hq));
;           const bf16x8 xf2 = *(const bf16x8*)(stb + swz128(lq, 2 * kk + hq));
;           ao = MFMA(xf2, yf2, ao);
;         }
;         const int l = 32 * lt + l31;
;         const float eo = __expf(cAcs[l]);
	s_andn2_b64 vcc, exec, s[82:83]
	v_bitop3_b32 v20, v174, v197, 15 bitop3:0x6c
	v_lshlrev_b32_e32 v199, 8, v174
	v_lshlrev_b32_e32 v24, 4, v20
	v_add_lshl_u32 v198, v174, v183, 8
	s_add_i32 s91, 0, 0x18000
	s_lshl_b32 s90, s90, 13
	s_add_i32 s90, s90, 0
	s_add_i32 s90, s90, 0x1c000
	v_add_u32_e32 v250, v24, v198
	v_add_u32_e32 v251, v24, v199
	v_add_u32_e32 v230, s90, v251
	v_add_u32_e32 v251, s91, v251
	ds_read_b128 v[20:23], v250
	ds_read_b128 v[24:27], v251
	ds_read_b128 v[36:39], v250 offset:32768
	ds_read_b128 v[40:43], v230
	v_xor_b32_e32 v231, 0x20, v250
	ds_read_b128 v[222:225], v231
	v_xor_b32_e32 v231, 0x20, v251
	ds_read_b128 v[226:229], v231
	v_xor_b32_e32 v231, 0x20, v250
	ds_read_b128 v[234:237], v231 offset:32768
	v_xor_b32_e32 v231, 0x20, v230
	ds_read_b128 v[238:241], v231
	v_xor_b32_e32 v231, 0x40, v250
	ds_read_b128 v[242:245], v231
	v_xor_b32_e32 v231, 0x40, v251
	ds_read_b128 v[246:249], v231
	s_waitcnt lgkmcnt(8)
	v_mfma_f32_32x32x16_bf16 v[20:35], v[24:27], v[20:23], 0
	v_lshlrev_b32_e32 v4, 16, v158
	v_and_b32_e32 v5, 0xffff0000, v158
	v_lshlrev_b32_e32 v6, 16, v159
	v_and_b32_e32 v7, 0xffff0000, v159
	v_mul_f32_e32 v96, 0xbfb8aa3b, v4
	v_mul_f32_e32 v97, 0xbfb8aa3b, v5
	s_waitcnt lgkmcnt(6)
	v_mfma_f32_32x32x16_bf16 v[36:51], v[40:43], v[36:39], 0
	v_mul_f32_e32 v98, 0xbfb8aa3b, v6
	v_mul_f32_e32 v99, 0xbfb8aa3b, v7
	v_exp_f32_e32 v96, v96
	v_exp_f32_e32 v97, v97
	v_exp_f32_e32 v98, v98
	v_exp_f32_e32 v99, v99
	s_waitcnt lgkmcnt(4)
	v_mfma_f32_32x32x16_bf16 v[20:35], v[226:229], v[222:225], v[20:35]
	v_add_f32_e32 v96, 1.0, v96
	v_add_f32_e32 v97, 1.0, v97
	v_add_f32_e32 v98, 1.0, v98
	v_add_f32_e32 v99, 1.0, v99
	v_rcp_f32_e32 v96, v96
	v_xor_b32_e32 v231, 0x40, v250
	ds_read_b128 v[222:225], v231 offset:32768
	v_xor_b32_e32 v231, 0x40, v230
	ds_read_b128 v[226:229], v231
	s_waitcnt lgkmcnt(4)
	v_mfma_f32_32x32x16_bf16 v[36:51], v[238:241], v[234:237], v[36:51]
	v_rcp_f32_e32 v97, v97
	v_rcp_f32_e32 v98, v98
	v_rcp_f32_e32 v99, v99
	v_pk_mul_f32 v[4:5], v[96:97], v[4:5]
	v_pk_mul_f32 v[6:7], v[98:99], v[6:7]
	v_xor_b32_e32 v231, 0x60, v250
	ds_read_b128 v[234:237], v231
	v_xor_b32_e32 v231, 0x60, v251
	ds_read_b128 v[238:241], v231
	s_waitcnt lgkmcnt(4)
	v_mfma_f32_32x32x16_bf16 v[20:35], v[246:249], v[242:245], v[20:35]
	v_lshlrev_b32_e32 v8, 16, v160
	v_and_b32_e32 v9, 0xffff0000, v160
	v_lshlrev_b32_e32 v10, 16, v161
	v_and_b32_e32 v11, 0xffff0000, v161
	v_mul_f32_e32 v96, 0xbfb8aa3b, v8
	v_mul_f32_e32 v97, 0xbfb8aa3b, v9
	v_xor_b32_e32 v231, 0x60, v250
	ds_read_b128 v[242:245], v231 offset:32768
	v_xor_b32_e32 v231, 0x60, v230
	ds_read_b128 v[246:249], v231
	s_waitcnt lgkmcnt(4)
	v_mfma_f32_32x32x16_bf16 v[36:51], v[226:229], v[222:225], v[36:51]
	v_mul_f32_e32 v98, 0xbfb8aa3b, v10
	v_mul_f32_e32 v99, 0xbfb8aa3b, v11
	v_exp_f32_e32 v96, v96
	v_exp_f32_e32 v97, v97
	v_exp_f32_e32 v98, v98
	v_exp_f32_e32 v99, v99
	v_xor_b32_e32 v231, 0x80, v250
	ds_read_b128 v[222:225], v231
	v_xor_b32_e32 v231, 0x80, v251
	ds_read_b128 v[226:229], v231
	s_waitcnt lgkmcnt(4)
	v_mfma_f32_32x32x16_bf16 v[20:35], v[238:241], v[234:237], v[20:35]
	v_add_f32_e32 v96, 1.0, v96
	v_add_f32_e32 v97, 1.0, v97
	v_add_f32_e32 v98, 1.0, v98
	v_add_f32_e32 v99, 1.0, v99
	v_rcp_f32_e32 v96, v96
	v_xor_b32_e32 v231, 0x80, v250
	ds_read_b128 v[234:237], v231 offset:32768
	v_xor_b32_e32 v231, 0x80, v230
	ds_read_b128 v[238:241], v231
	s_waitcnt lgkmcnt(4)
	v_mfma_f32_32x32x16_bf16 v[36:51], v[246:249], v[242:245], v[36:51]
	v_rcp_f32_e32 v97, v97
	v_rcp_f32_e32 v98, v98
	v_rcp_f32_e32 v99, v99
	v_pk_mul_f32 v[8:9], v[96:97], v[8:9]
	v_pk_mul_f32 v[10:11], v[98:99], v[10:11]
	v_xor_b32_e32 v231, 0xa0, v250
	ds_read_b128 v[242:245], v231
	v_xor_b32_e32 v231, 0xa0, v251
	ds_read_b128 v[246:249], v231
	s_waitcnt lgkmcnt(4)
	v_mfma_f32_32x32x16_bf16 v[20:35], v[226:229], v[222:225], v[20:35]
	v_lshlrev_b32_e32 v12, 16, v162
	v_and_b32_e32 v13, 0xffff0000, v162
	v_lshlrev_b32_e32 v14, 16, v163
	v_and_b32_e32 v15, 0xffff0000, v163
	v_mul_f32_e32 v96, 0xbfb8aa3b, v12
	v_mul_f32_e32 v97, 0xbfb8aa3b, v13
	v_xor_b32_e32 v231, 0xa0, v250
	ds_read_b128 v[222:225], v231 offset:32768
	v_xor_b32_e32 v231, 0xa0, v230
	ds_read_b128 v[226:229], v231
	s_waitcnt lgkmcnt(4)
	v_mfma_f32_32x32x16_bf16 v[36:51], v[238:241], v[234:237], v[36:51]
	v_mul_f32_e32 v98, 0xbfb8aa3b, v14
	v_mul_f32_e32 v99, 0xbfb8aa3b, v15
	v_exp_f32_e32 v96, v96
	v_exp_f32_e32 v97, v97
	v_exp_f32_e32 v98, v98
	v_exp_f32_e32 v99, v99
	v_xor_b32_e32 v231, 0xc0, v250
	ds_read_b128 v[234:237], v231
	v_xor_b32_e32 v231, 0xc0, v251
	ds_read_b128 v[238:241], v231
	s_waitcnt lgkmcnt(4)
	v_mfma_f32_32x32x16_bf16 v[20:35], v[246:249], v[242:245], v[20:35]
	v_add_f32_e32 v96, 1.0, v96
	v_add_f32_e32 v97, 1.0, v97
	v_add_f32_e32 v98, 1.0, v98
	v_add_f32_e32 v99, 1.0, v99
	v_rcp_f32_e32 v96, v96
	v_xor_b32_e32 v231, 0xc0, v250
	ds_read_b128 v[242:245], v231 offset:32768
	v_xor_b32_e32 v231, 0xc0, v230
	ds_read_b128 v[246:249], v231
	s_waitcnt lgkmcnt(4)
	v_mfma_f32_32x32x16_bf16 v[36:51], v[226:229], v[222:225], v[36:51]
	v_rcp_f32_e32 v97, v97
	v_rcp_f32_e32 v98, v98
	v_rcp_f32_e32 v99, v99
	v_pk_mul_f32 v[12:13], v[96:97], v[12:13]
	v_pk_mul_f32 v[14:15], v[98:99], v[14:15]
	v_xor_b32_e32 v231, 0xe0, v250
	ds_read_b128 v[222:225], v231
	v_xor_b32_e32 v231, 0xe0, v251
	ds_read_b128 v[226:229], v231
	s_waitcnt lgkmcnt(4)
	v_mfma_f32_32x32x16_bf16 v[20:35], v[238:241], v[234:237], v[20:35]
	v_lshlrev_b32_e32 v16, 16, v2
	v_and_b32_e32 v17, 0xffff0000, v2
	v_lshlrev_b32_e32 v18, 16, v3
	v_and_b32_e32 v19, 0xffff0000, v3
	v_mul_f32_e32 v96, 0xbfb8aa3b, v16
	v_mul_f32_e32 v97, 0xbfb8aa3b, v17
	v_xor_b32_e32 v231, 0xe0, v250
	ds_read_b128 v[234:237], v231 offset:32768
	v_xor_b32_e32 v231, 0xe0, v230
	ds_read_b128 v[238:241], v231
	v_lshl_add_u32 v174, v187, 2, s88
	ds_read_b32 v174, v174
	v_mov_b64_e32 v[198:199], s[72:73]
	v_mad_u64_u32 v[198:199], s[90:91], v172, s96, v[198:199]
	v_mad_i32_i24 v199, v173, s96, v199
	v_lshl_add_u64 v[172:173], v[198:199], 0, v[0:1]
	s_waitcnt lgkmcnt(5)
	v_mfma_f32_32x32x16_bf16 v[36:51], v[246:249], v[242:245], v[36:51]
	v_mul_f32_e32 v98, 0xbfb8aa3b, v18
	v_mul_f32_e32 v99, 0xbfb8aa3b, v19
	v_exp_f32_e32 v96, v96
	v_exp_f32_e32 v97, v97
	v_exp_f32_e32 v98, v98
	v_exp_f32_e32 v99, v99
	s_waitcnt lgkmcnt(3)
	v_mfma_f32_32x32x16_bf16 v[20:35], v[226:229], v[222:225], v[20:35]
	v_add_f32_e32 v96, 1.0, v96
	v_add_f32_e32 v97, 1.0, v97
	v_add_f32_e32 v98, 1.0, v98
	v_add_f32_e32 v99, 1.0, v99
	v_rcp_f32_e32 v96, v96
	s_waitcnt lgkmcnt(0)
	v_mul_f32_e32 v174, 0x3fb8aa3b, v174
	v_mfma_f32_32x32x16_bf16 v[36:51], v[238:241], v[234:237], v[36:51]
	v_rcp_f32_e32 v97, v97
	v_rcp_f32_e32 v98, v98
	v_rcp_f32_e32 v99, v99
	v_pk_mul_f32 v[16:17], v[96:97], v[16:17]
	v_pk_mul_f32 v[18:19], v[98:99], v[18:19]
	v_exp_f32_e32 v174, v174
	ds_read2_b64 v[222:225], v193 offset1:2
	ds_read2_b64 v[226:229], v193 offset0:4 offset1:6
	s_waitcnt lgkmcnt(0)

; DI unsigned pk2(float lo, float hi) { f32x2 v = {lo, hi}; bf2_t r = __builtin_convertvector(v, bf2_t); return __builtin_bit_cast(unsigned, r); }
; DI float bflo(unsigned u) { return __uint_as_float(u << 16); }
; DI float bfhi(unsigned u) { return __uint_as_float(u & 0xffff0000u); }
; DI float silu(float x) { return x * __builtin_amdgcn_rcpf(1.f + __expf(-x)); }
; #define LDS_BARRIER() do { asm volatile("s_waitcnt lgkmcnt(0)" ::: "memory"); __builtin_amdgcn_s_barrier(); asm volatile("" ::: "memory"); } while (0)
; DI void ssd_scan_phase(bf16_t* P, const bf16_t* BT, const bf16_t* Cc, const bf16_t* CB, const float* dt, const float* acs,
;                        const float* cw, const float* cb, const float* Dp, char* lds, bool dry, int mode, float* Sbuf) {
;     ...
;         const int l = 32 * lt + l31;
;         const float eo = __expf(cAcs[l]);
;         bf16_t* Zq = P + t0 * 5120 + pcol;
; #pragma unroll
;         for (int gi = 0; gi < 4; ++gi) {
;           const int p0 = 8 * gi + 4 * h;
;           const u32x2 xsv = *(const u32x2*)(sXs + l * 80 + p0 * 2);
;           const u32x2 zv = cz[gi];
;           const float xs0 = bflo(xsv[0]), xs1 = bfhi(xsv[0]), xs2 = bflo(xsv[1]), xs3 = bfhi(xsv[1]);
;           const float z0 = bflo(zv[0]), z1 = bfhi(zv[0]), z2 = bflo(zv[1]), z3 = bfhi(zv[1]);
;           const float y0 = (ad[4 * gi] + eo * ao[4 * gi] + Dh * xs0) * silu(z0);
;           const float y1 = (ad[4 * gi + 1] + eo * ao[4 * gi + 1] + Dh * xs1) * silu(z1);
;           const float y2 = (ad[4 * gi + 2] + eo * ao[4 * gi + 2] + Dh * xs2) * silu(z2);
;           const float y3 = (ad[4 * gi + 3] + eo * ao[4 * gi + 3] + Dh * xs3) * silu(z3);
;           u32x2 ov; ov[0] = pk2(y0, y1); ov[1] = pk2(y2, y3);
;           if (!dry) *(u32x2*)(Zq + zoff + 8 * gi) = ov;
;         }
;         if (c + 1 < c1) {
; #pragma unroll
;           for (int gi = 0; gi < 4; ++gi) cz[gi] = *(const u32x2*)(Zq + 128 * 5120 + zoff + 8 * gi);
;         }
;     ...
;       if (tid < 128) { sAcs[((c + 1) & 1) * 128 + tid] = racs; sDt[((c + 1) & 1) * 128 + tid] = rdt; }
;       racs = nacs; rdt = ndt;
;       LDS_BARRIER();
.LBB0_1109:
	s_or_b64 exec, exec, s[80:81]
	v_add_u32_e32 v230, 0x80, v170
	s_and_saveexec_b64 s[80:81], s[50:51]
	s_xor_b64 s[80:81], exec, s[80:81]
	v_add_u32_e32 v170, 0x80, v170
	s_andn2_saveexec_b64 s[80:81], s[80:81]
	s_cbranch_execz .LBB0_1113
	v_and_b32_e32 v231, 0x80, v230
	v_add_u32_e32 v231, v231, v127
	v_lshl_add_u32 v231, v231, 2, 0
	v_add_u32_e32 v250, 0x22c00, v231
	v_add_u32_e32 v231, 0x22800, v231
	v_mov_b32_e32 v170, v230
	ds_write_b32 v231, v194
	ds_write_b32 v250, v195
.LBB0_1113:
	s_or_b64 exec, exec, s[80:81]
	s_add_u32 s74, s74, 0x20000
	s_waitcnt lgkmcnt(0)
	s_barrier
	s_addc_u32 s75, s75, 0
	s_add_u32 s76, s76, 0x20000
	s_addc_u32 s77, s77, 0
	s_addk_i32 s85, 0x2000
	s_cmp_lg_u64 s[42:43], 0
	s_cbranch_scc1 .Ldefer_done
	s_cmp_lg_u64 s[56:57], 0
	s_cbranch_scc1 .Ldefer_done
	v_pk_fma_f32 v[20:21], v[36:37], v[174:175], v[20:21] op_sel_hi:[1,0,1]
	v_pk_fma_f32 v[22:23], v[38:39], v[174:175], v[22:23] op_sel_hi:[1,0,1]
	v_pk_fma_f32 v[24:25], v[40:41], v[174:175], v[24:25] op_sel_hi:[1,0,1]
	v_pk_fma_f32 v[26:27], v[42:43], v[174:175], v[26:27] op_sel_hi:[1,0,1]
	v_pk_fma_f32 v[28:29], v[44:45], v[174:175], v[28:29] op_sel_hi:[1,0,1]
	v_pk_fma_f32 v[30:31], v[46:47], v[174:175], v[30:31] op_sel_hi:[1,0,1]
	v_pk_fma_f32 v[32:33], v[48:49], v[174:175], v[32:33] op_sel_hi:[1,0,1]
	v_pk_fma_f32 v[34:35], v[50:51], v[174:175], v[34:35] op_sel_hi:[1,0,1]
	v_lshlrev_b32_e32 v36, 16, v222
	v_and_b32_e32 v37, 0xffff0000, v222
	v_lshlrev_b32_e32 v38, 16, v223
	v_and_b32_e32 v39, 0xffff0000, v223
	v_pk_fma_f32 v[20:21], v[156:157], v[36:37], v[20:21]
	v_pk_fma_f32 v[22:23], v[156:157], v[38:39], v[22:23]
	v_pk_mul_f32 v[20:21], v[4:5], v[20:21]
	v_pk_mul_f32 v[22:23], v[6:7], v[22:23]
	v_cvt_pk_bf16_f32 v20, v20, v21
	v_cvt_pk_bf16_f32 v21, v22, v23
	global_store_dwordx2 v[172:173], v[20:21], off
	v_lshlrev_b32_e32 v40, 16, v224
	v_and_b32_e32 v41, 0xffff0000, v224
	v_lshlrev_b32_e32 v42, 16, v225
	v_and_b32_e32 v43, 0xffff0000, v225
	v_pk_fma_f32 v[24:25], v[156:157], v[40:41], v[24:25]
	v_pk_fma_f32 v[26:27], v[156:157], v[42:43], v[26:27]
	v_pk_mul_f32 v[24:25], v[8:9], v[24:25]
	v_pk_mul_f32 v[26:27], v[10:11], v[26:27]
	v_cvt_pk_bf16_f32 v24, v24, v25
	v_cvt_pk_bf16_f32 v25, v26, v27
	global_store_dwordx2 v[172:173], v[24:25], off offset:16
	v_lshlrev_b32_e32 v36, 16, v226
	v_and_b32_e32 v37, 0xffff0000, v226
	v_lshlrev_b32_e32 v38, 16, v227
	v_and_b32_e32 v39, 0xffff0000, v227
	v_pk_fma_f32 v[28:29], v[156:157], v[36:37], v[28:29]
	v_pk_fma_f32 v[30:31], v[156:157], v[38:39], v[30:31]
	v_pk_mul_f32 v[28:29], v[12:13], v[28:29]
	v_pk_mul_f32 v[30:31], v[14:15], v[30:31]
	v_cvt_pk_bf16_f32 v28, v28, v29
	v_cvt_pk_bf16_f32 v29, v30, v31
	global_store_dwordx2 v[172:173], v[28:29], off offset:32
	v_lshlrev_b32_e32 v40, 16, v228
	v_and_b32_e32 v41, 0xffff0000, v228
	v_lshlrev_b32_e32 v42, 16, v229
	v_and_b32_e32 v43, 0xffff0000, v229
	v_pk_fma_f32 v[32:33], v[156:157], v[40:41], v[32:33]
	v_pk_fma_f32 v[34:35], v[156:157], v[42:43], v[34:35]
	v_pk_mul_f32 v[32:33], v[16:17], v[32:33]
	v_pk_mul_f32 v[34:35], v[18:19], v[34:35]
	v_cvt_pk_bf16_f32 v32, v32, v33
	v_cvt_pk_bf16_f32 v33, v34, v35
	global_store_dwordx2 v[172:173], v[32:33], off offset:48
	s_and_b64 vcc, exec, s[78:79]
	s_cbranch_vccnz .Ldefer_done
	s_mov_b64 s[82:83], 0x140000
	v_add_co_u32_e32 v20, vcc, 0x140000, v172
	v_lshl_add_u64 v[2:3], v[172:173], 0, s[82:83]
	s_nop 0
	v_addc_co_u32_e32 v21, vcc, 0, v173, vcc
	global_load_dwordx2 v[158:159], v[20:21], off
	global_load_dwordx2 v[160:161], v[2:3], off offset:16
	global_load_dwordx2 v[162:163], v[2:3], off offset:32
	s_nop 0
	global_load_dwordx2 v[2:3], v[2:3], off offset:48
.Ldefer_done:
	s_and_b64 vcc, exec, s[78:79]
	s_cbranch_vccnz .LBB0_1119
	s_cmp_lg_u64 s[56:57], 0
	s_cbranch_scc1 .Lscan_end_m1
	s_waitcnt vmcnt(16)
	s_branch .Lscan_end_done
